# grid barrier: workgroups that are not last in their XCD wait on the top generation word directly (one hop less)
# speedup vs baseline: 1.0071x; 1.0071x over previous
.LBB0_43:
	s_or_b64 exec, exec, s[28:29]
	v_cvt_f32_u32_e32 v4, v2
	s_waitcnt vmcnt(0)
	v_readfirstlane_b32 s2, v3
	v_sub_u32_e32 v3, 0, v2
	v_rcp_iflag_f32_e32 v4, v4
	v_add_u32_e32 v5, s2, v1
	v_mul_f32_e32 v4, 0x4f7ffffe, v4
	v_cvt_u32_f32_e32 v4, v4
	v_mul_lo_u32 v1, v3, v4
	v_mul_hi_u32 v1, v4, v1
	v_add_u32_e32 v1, v4, v1
	v_mul_hi_u32 v1, v5, v1
	v_mul_lo_u32 v3, v1, v2
	v_sub_u32_e32 v3, v5, v3
	v_add_u32_e32 v4, 1, v1
	v_sub_u32_e32 v6, v3, v2
	v_cmp_ge_u32_e32 vcc, v3, v2
	s_nop 1
	v_cndmask_b32_e32 v1, v1, v4, vcc
	v_cndmask_b32_e32 v3, v3, v6, vcc
	v_add_u32_e32 v4, 1, v1
	v_cmp_ge_u32_e32 vcc, v3, v2
	v_add_u32_e32 v3, 1, v5
	s_nop 0
	v_cndmask_b32_e32 v1, v1, v4, vcc
	v_mul_lo_u32 v4, v2, v1
	v_add_u32_e32 v2, v4, v2
	v_cmp_ne_u32_e32 vcc, v3, v2
	s_and_saveexec_b64 s[2:3], vcc
	s_xor_b64 s[28:29], exec, s[2:3]
	s_cbranch_execz .LBB0_57
	v_readlane_b32 s2, v253, 26
	v_readlane_b32 s3, v253, 27
	s_waitcnt lgkmcnt(0)
	s_nop 3
	global_load_dword v0, v177, s[2:3] sc1
	s_waitcnt vmcnt(0)
	v_cmp_eq_u32_e32 vcc, v0, v1
	s_and_saveexec_b64 s[38:39], vcc
	s_cbranch_execz .LBB0_56
	s_mov_b32 s2, 1
	s_mov_b64 s[40:41], 0
	s_branch .LBB0_47

.LBB0_49:
	v_readlane_b32 s6, v253, 26
	v_readlane_b32 s7, v253, 27
	s_add_i32 s2, s2, 1
	s_mov_b64 s[46:47], -1
	s_nop 2
	global_load_dword v0, v177, s[6:7] sc1
	s_waitcnt vmcnt(0)
	v_cmp_ne_u32_e32 vcc, v0, v1
	s_orn2_b64 s[44:45], vcc, exec
	s_branch .LBB0_46
